# rare-path-only cross-half max exchange in MLA and NSA online softmax: common path is 8 max3 plus one compare against a per-lane threshold
# baseline (speedup 1.0000x reference)
; DI float xhalf_max(float v) { unsigned a = __builtin_bit_cast(unsigned, v), b = a; swap32(a, b); return fmaxf(__builtin_bit_cast(float, a), __builtin_bit_cast(float, b)); }
; DI float fexp2(float x) { return __builtin_amdgcn_exp2f(x); }
; DI void mla_unit(const Params& p, LAS unsigned char* lds, int b, int h, int qb, int tid) {
;     ...
;                 float mx = max16(s);
;                 mx = xhalf_max(mx);
;                 const float mn = (mx > m + 8.f) ? mx : m, alpha = fexp2(m - mn); m = mn; l *= alpha;
;                 if (__any(alpha != 1.f)) {
; #pragma unroll
;                     for (int db = 0; db < 4; ++db) o[db] = o[db] * alpha;
;                 }
.Lmla_nomask_0:
	v_max3_f32 v236, v64, v65, v66
	v_max3_f32 v237, v67, v68, v69
	v_max3_f32 v238, v70, v71, v72
	v_max3_f32 v239, v73, v74, v75
	v_max3_f32 v236, v236, v76, v77
	v_max3_f32 v237, v237, v78, v79
	v_max3_f32 v236, v236, v237, v238
	v_max3_f32 v236, v236, v239, v239
	v_cmp_gt_f32_e32 vcc, v236, v235
	s_cbranch_vccz .Lmla_norescale_0
	v_mov_b32_e32 v237, v236
	s_nop 1
	v_permlane32_swap_b32_e32 v236, v237
	s_nop 0
	v_max_f32_e32 v236, v236, v237
	v_cmp_gt_f32_e32 vcc, v236, v235
	v_sub_f32_e32 v236, v236, v240
	s_nop 0
	v_cndmask_b32_e32 v237, v180, v236, vcc
	v_sub_f32_e32 v166, v180, v237
	v_mov_b32_e32 v180, v237
	v_exp_f32_e32 v166, v166
	s_nop 0
	v_mul_f32_e32 v155, v155, v166
	v_pk_mul_f32 v[62:63], v[62:63], v[166:167] op_sel_hi:[1,0]
	v_pk_mul_f32 v[60:61], v[60:61], v[166:167] op_sel_hi:[1,0]
	v_pk_mul_f32 v[58:59], v[58:59], v[166:167] op_sel_hi:[1,0]
	v_pk_mul_f32 v[56:57], v[56:57], v[166:167] op_sel_hi:[1,0]
	v_pk_mul_f32 v[54:55], v[54:55], v[166:167] op_sel_hi:[1,0]
	v_pk_mul_f32 v[52:53], v[52:53], v[166:167] op_sel_hi:[1,0]
	v_pk_mul_f32 v[50:51], v[50:51], v[166:167] op_sel_hi:[1,0]
	v_pk_mul_f32 v[48:49], v[48:49], v[166:167] op_sel_hi:[1,0]
	v_pk_mul_f32 v[46:47], v[46:47], v[166:167] op_sel_hi:[1,0]
	v_pk_mul_f32 v[44:45], v[44:45], v[166:167] op_sel_hi:[1,0]
	v_pk_mul_f32 v[42:43], v[42:43], v[166:167] op_sel_hi:[1,0]
	v_pk_mul_f32 v[40:41], v[40:41], v[166:167] op_sel_hi:[1,0]
	v_pk_mul_f32 v[38:39], v[38:39], v[166:167] op_sel_hi:[1,0]
	v_pk_mul_f32 v[36:37], v[36:37], v[166:167] op_sel_hi:[1,0]
	v_pk_mul_f32 v[34:35], v[34:35], v[166:167] op_sel_hi:[1,0]
	v_pk_mul_f32 v[32:33], v[32:33], v[166:167] op_sel_hi:[1,0]
	v_pk_mul_f32 v[30:31], v[30:31], v[166:167] op_sel_hi:[1,0]
	v_pk_mul_f32 v[28:29], v[28:29], v[166:167] op_sel_hi:[1,0]
	v_pk_mul_f32 v[26:27], v[26:27], v[166:167] op_sel_hi:[1,0]
	v_pk_mul_f32 v[24:25], v[24:25], v[166:167] op_sel_hi:[1,0]
	v_pk_mul_f32 v[22:23], v[22:23], v[166:167] op_sel_hi:[1,0]
	v_pk_mul_f32 v[20:21], v[20:21], v[166:167] op_sel_hi:[1,0]
	v_pk_mul_f32 v[18:19], v[18:19], v[166:167] op_sel_hi:[1,0]
	v_pk_mul_f32 v[16:17], v[16:17], v[166:167] op_sel_hi:[1,0]
	v_pk_mul_f32 v[14:15], v[14:15], v[166:167] op_sel_hi:[1,0]
	v_pk_mul_f32 v[12:13], v[12:13], v[166:167] op_sel_hi:[1,0]
	v_pk_mul_f32 v[10:11], v[10:11], v[166:167] op_sel_hi:[1,0]
	v_pk_mul_f32 v[8:9], v[8:9], v[166:167] op_sel_hi:[1,0]
	v_pk_mul_f32 v[6:7], v[6:7], v[166:167] op_sel_hi:[1,0]
	v_pk_mul_f32 v[4:5], v[4:5], v[166:167] op_sel_hi:[1,0]
	v_pk_mul_f32 v[2:3], v[2:3], v[166:167] op_sel_hi:[1,0]
	v_pk_mul_f32 v[0:1], v[0:1], v[166:167] op_sel_hi:[1,0]
	v_cmp_lt_f32_e32 vcc, 0xdf0ac723, v180
	v_mov_b32_e32 v237, 0x41000000
	v_mov_b32_e32 v236, 0xe0ad78ec
	v_cndmask_b32_e32 v238, 0, v180, vcc
	v_cndmask_b32_e32 v235, v236, v237, vcc
	v_add_f32_e32 v239, v238, v240
	v_sub_f32_e32 v240, v240, v239
	v_sub_f32_e32 v241, v241, v239
	v_sub_f32_e32 v242, v242, v239
	v_sub_f32_e32 v243, v243, v239
	v_sub_f32_e32 v244, v244, v239
	v_sub_f32_e32 v245, v245, v239
	v_sub_f32_e32 v246, v246, v239
	v_sub_f32_e32 v247, v247, v239
	v_sub_f32_e32 v248, v248, v239
	v_sub_f32_e32 v249, v249, v239
	v_sub_f32_e32 v250, v250, v239
	v_sub_f32_e32 v251, v251, v239
	v_sub_f32_e32 v252, v252, v239
	v_sub_f32_e32 v253, v253, v239
	v_sub_f32_e32 v254, v254, v239
	v_sub_f32_e32 v255, v255, v239
	v_sub_f32_e32 v64, v64, v239
	v_sub_f32_e32 v65, v65, v239
	v_sub_f32_e32 v66, v66, v239
	v_sub_f32_e32 v67, v67, v239
	v_sub_f32_e32 v68, v68, v239
	v_sub_f32_e32 v69, v69, v239
	v_sub_f32_e32 v70, v70, v239
	v_sub_f32_e32 v71, v71, v239
	v_sub_f32_e32 v72, v72, v239
	v_sub_f32_e32 v73, v73, v239
	v_sub_f32_e32 v74, v74, v239
	v_sub_f32_e32 v75, v75, v239
	v_sub_f32_e32 v76, v76, v239
	v_sub_f32_e32 v77, v77, v239
	v_sub_f32_e32 v78, v78, v239
	v_sub_f32_e32 v79, v79, v239

; #define LAS __attribute__((address_space(3)))
; #define ST_V(base, v) do { LAS unsigned char* vp_ = (base) + voff; *(LAS u32x2*)vp_ = (u32x2){(v).x, (v).y}; *(LAS u32x2*)(vp_ + 8) = (u32x2){(v).z, (v).w}; } while (0)
; DI void nsa_unit(const Params& p, LAS unsigned char* lds, unsigned char* ldsg, int bg, int qt, int tid) {
;     ...
;         f32x16 o[2];
; #pragma unroll
;         for (int db = 0; db < 2; ++db)
; #pragma unroll
;             for (int i = 0; i < 16; ++i) o[db][i] = 0.f;
;         float m = -1e20f, l = 0.f;
;         u32x4 rk1, rv1, rk2, rv2;
;         { const int nb = LIST[0]; rk1 = *(const u32x4*)(Ksrc + (size_t)(64 * nb) * NPROJ); rv1 = *(const u32x4*)(Vsrc + 64 * nb); }
;         *(LAS u32x4*)(lds + toff) = rk1; ST_V(lds, rv1);
;         if (nl > 1) { const int nb = LIST[1]; rk1 = *(const u32x4*)(Ksrc + (size_t)(64 * nb) * NPROJ); rv1 = *(const u32x4*)(Vsrc + 64 * nb); }
;         __syncthreads();
;         int cb = 0;
.LBB0_818:
	s_movk_i32 s2, 0x88
	s_cmp_lt_i32 s8, 1
	v_mul_u32_u24_e32 v15, 0x88, v68
	v_mad_u32_u24 v176, v68, s2, v168
	s_waitcnt lgkmcnt(0)
	s_barrier
	s_cbranch_scc1 .LBB0_839
	v_or_b32_e32 v10, s49, v67
	s_add_i32 s2, 0, 0x26400
	v_lshl_add_u32 v113, v10, 4, s2
	v_lshlrev_b32_e32 v10, 2, v114
	v_mov_b32_e32 v175, 0
	v_sub_u32_e32 v117, v150, v10
	v_mov_b32_e32 v153, v152
	v_mov_b32_e32 v118, 0xe0ad78ec
	v_mov_b32_e32 v252, 0xe0ad78ec
	v_mov_b32_e32 v248, 0
	s_mov_b32 s9, 0
	v_readlane_b32 s10, v234, 35
	s_mov_b32 s11, 0
	v_mov_b32_e32 v48, 0
	v_mov_b32_e32 v49, v175
	v_mov_b32_e32 v50, v175
	v_mov_b32_e32 v51, v175
	v_mov_b32_e32 v52, v175
	v_mov_b32_e32 v53, v175
	v_mov_b32_e32 v54, v175
	v_mov_b32_e32 v55, v175
	v_mov_b32_e32 v56, v175
	v_mov_b32_e32 v57, v175
	v_mov_b32_e32 v58, v175
	v_mov_b32_e32 v59, v175
	v_mov_b32_e32 v60, v175
	v_mov_b32_e32 v61, v175
	v_mov_b32_e32 v62, v175
	v_mov_b32_e32 v63, v175
	v_mov_b32_e32 v64, v175
	v_mov_b32_e32 v65, v175
	v_mov_b32_e32 v66, v175
	v_mov_b32_e32 v67, v175
	v_mov_b32_e32 v68, v175
	v_mov_b32_e32 v69, v175
	v_mov_b32_e32 v70, v175
	v_mov_b32_e32 v71, v175
	v_mov_b32_e32 v72, v175
	v_mov_b32_e32 v73, v175
	v_mov_b32_e32 v74, v175
	v_mov_b32_e32 v75, v175
	v_mov_b32_e32 v76, v175
	v_mov_b32_e32 v77, v175
	v_mov_b32_e32 v78, v175
	v_mov_b32_e32 v79, v175

; DI float xhalf_max(float v) { unsigned a = __builtin_bit_cast(unsigned, v), b = a; swap32(a, b); return fmaxf(__builtin_bit_cast(float, a), __builtin_bit_cast(float, b)); }
; DI float fexp2(float x) { return __builtin_amdgcn_exp2f(x); }
; template <int MODE>
; DI void nsa_tile(LAS const unsigned char* buf, const bf16x8 (&qf)[4], f32x16 (&o)[2], float& m, float& l, int kbase0, int t, bool lanesel, float slope2, int c, int hi) {
;     ...
;         float mx = max16(s);
;         mx = xhalf_max(mx);
;         if (__any(mx > m + 8.f)) {
;             const float mn = fmaxf(m, mx), alpha = fexp2(m - mn); m = mn; l *= alpha;
;             o[0] = o[0] * alpha; o[1] = o[1] * alpha;
;         }
.LBB0_826:
	v_max3_f32 v120, v80, v81, v82
	v_max3_f32 v121, v83, v84, v85
	v_max3_f32 v122, v86, v87, v88
	v_max3_f32 v123, v89, v90, v91
	s_nop 0
	v_max3_f32 v120, v120, v92, v93
	v_max3_f32 v121, v121, v94, v95
	s_nop 0
	v_max3_f32 v120, v120, v121, v122
	s_nop 0
	v_max3_f32 v120, v120, v123, v123
	s_nop 0
	v_cmp_gt_f32_e32 vcc, v120, v252
	s_cbranch_vccz .LBB0_828
	v_mov_b32_e32 v121, v120
	s_nop 1
	v_permlane32_swap_b32 v120, v121
	s_nop 0
	v_max_f32_e32 v120, v120, v121
	v_add_f32_e32 v120, v120, v248
	v_max_f32_e32 v120, v120, v120
	v_max_f32_e32 v121, v118, v118
	v_max_f32_e32 v120, v121, v120
	v_sub_f32_e32 v118, v118, v120
	v_exp_f32_e32 v118, v118
	s_nop 0
	v_mul_f32_e32 v175, v175, v118
	v_pk_mul_f32 v[78:79], v[78:79], v[118:119] op_sel_hi:[1,0]
	v_pk_mul_f32 v[76:77], v[76:77], v[118:119] op_sel_hi:[1,0]
	v_pk_mul_f32 v[74:75], v[74:75], v[118:119] op_sel_hi:[1,0]
	v_pk_mul_f32 v[72:73], v[72:73], v[118:119] op_sel_hi:[1,0]
	v_pk_mul_f32 v[70:71], v[70:71], v[118:119] op_sel_hi:[1,0]
	v_pk_mul_f32 v[68:69], v[68:69], v[118:119] op_sel_hi:[1,0]
	v_pk_mul_f32 v[66:67], v[66:67], v[118:119] op_sel_hi:[1,0]
	v_pk_mul_f32 v[64:65], v[64:65], v[118:119] op_sel_hi:[1,0]
	v_pk_mul_f32 v[62:63], v[62:63], v[118:119] op_sel_hi:[1,0]
	v_pk_mul_f32 v[60:61], v[60:61], v[118:119] op_sel_hi:[1,0]
	v_pk_mul_f32 v[58:59], v[58:59], v[118:119] op_sel_hi:[1,0]
	v_pk_mul_f32 v[56:57], v[56:57], v[118:119] op_sel_hi:[1,0]
	v_pk_mul_f32 v[54:55], v[54:55], v[118:119] op_sel_hi:[1,0]
	v_pk_mul_f32 v[52:53], v[52:53], v[118:119] op_sel_hi:[1,0]
	v_pk_mul_f32 v[50:51], v[50:51], v[118:119] op_sel_hi:[1,0]
	v_pk_mul_f32 v[48:49], v[48:49], v[118:119] op_sel_hi:[1,0]
	v_mov_b32_e32 v118, v120
	v_cmp_lt_f32_e32 vcc, 0xdf0ac723, v118
	s_nop 1
	v_cndmask_b32_e32 v250, 0, v118, vcc
	v_mov_b32_e32 v254, 0x41000000
	v_mov_b32_e32 v255, 0xe0ad78ec
	v_cndmask_b32_e32 v252, v255, v254, vcc
	v_sub_f32_e32 v251, v250, v248
	v_mov_b32_e32 v248, v250
	v_sub_f32_e32 v80, v80, v251
	v_sub_f32_e32 v81, v81, v251
	v_sub_f32_e32 v82, v82, v251
	v_sub_f32_e32 v83, v83, v251
	v_sub_f32_e32 v84, v84, v251
	v_sub_f32_e32 v85, v85, v251
	v_sub_f32_e32 v86, v86, v251
	v_sub_f32_e32 v87, v87, v251
	v_sub_f32_e32 v88, v88, v251
	v_sub_f32_e32 v89, v89, v251
	v_sub_f32_e32 v90, v90, v251
	v_sub_f32_e32 v91, v91, v251
	v_sub_f32_e32 v92, v92, v251
	v_sub_f32_e32 v93, v93, v251
	v_sub_f32_e32 v94, v94, v251
	v_sub_f32_e32 v95, v95, v251

; DI float xhalf_max(float v) { unsigned a = __builtin_bit_cast(unsigned, v), b = a; swap32(a, b); return fmaxf(__builtin_bit_cast(float, a), __builtin_bit_cast(float, b)); }
; DI float fexp2(float x) { return __builtin_amdgcn_exp2f(x); }
; template <int MODE>
; DI void nsa_tile(LAS const unsigned char* buf, const bf16x8 (&qf)[4], f32x16 (&o)[2], float& m, float& l, int kbase0, int t, bool lanesel, float slope2, int c, int hi) {
;     ...
;         float mx = max16(s);
;         mx = xhalf_max(mx);
;         if (__any(mx > m + 8.f)) {
;             const float mn = fmaxf(m, mx), alpha = fexp2(m - mn); m = mn; l *= alpha;
;             o[0] = o[0] * alpha; o[1] = o[1] * alpha;
;         }
.LBB0_832:
	v_max3_f32 v119, v80, v81, v82
	v_max3_f32 v120, v83, v84, v85
	v_max3_f32 v121, v86, v87, v88
	v_max3_f32 v122, v89, v90, v91
	s_nop 0
	v_max3_f32 v119, v119, v92, v93
	v_max3_f32 v120, v120, v94, v95
	s_nop 0
	v_max3_f32 v119, v119, v120, v121
	s_nop 0
	v_max3_f32 v119, v119, v122, v122
	s_nop 0
	v_cmp_gt_f32_e32 vcc, v119, v252
	s_cbranch_vccz .LBB0_834
	v_mov_b32_e32 v120, v119
	s_nop 1
	v_permlane32_swap_b32 v119, v120
	s_nop 0
	v_max_f32_e32 v119, v119, v120
	v_add_f32_e32 v119, v119, v248
	v_max_f32_e32 v119, v119, v119
	v_max_f32_e32 v120, v118, v118
	v_max_f32_e32 v119, v120, v119
	v_sub_f32_e32 v118, v118, v119
	v_exp_f32_e32 v118, v118
	s_nop 0
	v_mul_f32_e32 v175, v175, v118
	v_pk_mul_f32 v[78:79], v[78:79], v[118:119] op_sel_hi:[1,0]
	v_pk_mul_f32 v[76:77], v[76:77], v[118:119] op_sel_hi:[1,0]
	v_pk_mul_f32 v[74:75], v[74:75], v[118:119] op_sel_hi:[1,0]
	v_pk_mul_f32 v[72:73], v[72:73], v[118:119] op_sel_hi:[1,0]
	v_pk_mul_f32 v[70:71], v[70:71], v[118:119] op_sel_hi:[1,0]
	v_pk_mul_f32 v[68:69], v[68:69], v[118:119] op_sel_hi:[1,0]
	v_pk_mul_f32 v[66:67], v[66:67], v[118:119] op_sel_hi:[1,0]
	v_pk_mul_f32 v[64:65], v[64:65], v[118:119] op_sel_hi:[1,0]
	v_pk_mul_f32 v[62:63], v[62:63], v[118:119] op_sel_hi:[1,0]
	v_pk_mul_f32 v[60:61], v[60:61], v[118:119] op_sel_hi:[1,0]
	v_pk_mul_f32 v[58:59], v[58:59], v[118:119] op_sel_hi:[1,0]
	v_pk_mul_f32 v[56:57], v[56:57], v[118:119] op_sel_hi:[1,0]
	v_pk_mul_f32 v[54:55], v[54:55], v[118:119] op_sel_hi:[1,0]
	v_pk_mul_f32 v[52:53], v[52:53], v[118:119] op_sel_hi:[1,0]
	v_pk_mul_f32 v[50:51], v[50:51], v[118:119] op_sel_hi:[1,0]
	v_pk_mul_f32 v[48:49], v[48:49], v[118:119] op_sel_hi:[1,0]
	v_mov_b32_e32 v118, v119
	v_cmp_lt_f32_e32 vcc, 0xdf0ac723, v118
	s_nop 1
	v_cndmask_b32_e32 v250, 0, v118, vcc
	v_mov_b32_e32 v254, 0x41000000
	v_mov_b32_e32 v255, 0xe0ad78ec
	v_cndmask_b32_e32 v252, v255, v254, vcc
	v_sub_f32_e32 v251, v250, v248
	v_mov_b32_e32 v248, v250
	v_sub_f32_e32 v80, v80, v251
	v_sub_f32_e32 v81, v81, v251
	v_sub_f32_e32 v82, v82, v251
	v_sub_f32_e32 v83, v83, v251
	v_sub_f32_e32 v84, v84, v251
	v_sub_f32_e32 v85, v85, v251
	v_sub_f32_e32 v86, v86, v251
	v_sub_f32_e32 v87, v87, v251
	v_sub_f32_e32 v88, v88, v251
	v_sub_f32_e32 v89, v89, v251
	v_sub_f32_e32 v90, v90, v251
	v_sub_f32_e32 v91, v91, v251
	v_sub_f32_e32 v92, v92, v251
	v_sub_f32_e32 v93, v93, v251
	v_sub_f32_e32 v94, v94, v251
	v_sub_f32_e32 v95, v95, v251

; #define LAS __attribute__((address_space(3)))
; #define ST_V(base, v) do { LAS unsigned char* vp_ = (base) + voff; *(LAS u32x2*)vp_ = (u32x2){(v).x, (v).y}; *(LAS u32x2*)(vp_ + 8) = (u32x2){(v).z, (v).w}; } while (0)
; DI void nsa_unit(const Params& p, LAS unsigned char* lds, unsigned char* ldsg, int bg, int qt, int tid) {
;     ...
;         f32x16 o[2];
; #pragma unroll
;         for (int db = 0; db < 2; ++db)
; #pragma unroll
;             for (int i = 0; i < 16; ++i) o[db][i] = 0.f;
;         float m = -1e20f, l = 0.f;
;         u32x4 rk1, rv1, rk2, rv2;
;         rk1 = *(const u32x4*)(Ksrc + (size_t)(64 * kt_lo) * NPROJ); rv1 = *(const u32x4*)(Vsrc + 64 * kt_lo);
;         *(LAS u32x4*)(lds + toff) = rk1; ST_V(lds, rv1);
;         if (kt_lo < kt_hi) { rk1 = *(const u32x4*)(Ksrc + (size_t)(64 * (kt_lo + 1)) * NPROJ); rv1 = *(const u32x4*)(Vsrc + 64 * (kt_lo + 1)); }
;         __syncthreads();
;         int cb = 0;
.LBB0_842:
	s_cmp_le_u32 s7, s6
	s_mov_b64 s[2:3], -1
	s_waitcnt lgkmcnt(0)
	s_barrier
	s_cbranch_scc0 .LBB0_863
	v_lshlrev_b32_e32 v154, 2, v114
	s_add_i32 s2, s84, 0xfffffe01
	v_sub_u32_e32 v10, v115, v154
	s_and_b32 s8, s2, 0xffffffc0
	s_movk_i32 s2, 0x88
	v_subrev_u32_e32 v10, s56, v10
	v_mov_b32_e32 v94, v1
	v_mov_b32_e32 v95, v1
	v_mad_u64_u32 v[160:161], s[2:3], v116, s2, v[112:113]
	v_subrev_u32_e32 v10, s8, v10
	v_mov_b32_e32 v80, v1
	v_mov_b32_e32 v81, v1
	v_mov_b32_e32 v82, v1
	v_mov_b32_e32 v83, v1
	v_mov_b32_e32 v84, v1
	v_mov_b32_e32 v85, v1
	v_mov_b32_e32 v86, v1
	v_mov_b32_e32 v87, v1
	v_mov_b32_e32 v88, v1
	v_mov_b32_e32 v89, v1
	v_mov_b32_e32 v90, v1
	v_mov_b32_e32 v91, v1
	v_mov_b32_e32 v92, v1
	v_mov_b32_e32 v93, v1
	v_mov_b64_e32 v[110:111], v[94:95]
	s_addk_i32 s40, 0xfe01
	v_add_u32_e32 v178, 0xfffffe01, v150
	v_mov_b32_e32 v153, v152
	v_add_u32_e32 v179, 0x1fc0, v10
	s_mov_b32 s9, 0
	v_mov_b32_e32 v180, 0xe0ad78ec
	v_mov_b32_e32 v253, 0xe0ad78ec
	v_mov_b32_e32 v249, 0
	v_mov_b32_e32 v161, 0
	v_mov_b64_e32 v[108:109], v[92:93]
	v_mov_b64_e32 v[106:107], v[90:91]
	v_mov_b64_e32 v[104:105], v[88:89]
	v_mov_b64_e32 v[102:103], v[86:87]
	v_mov_b64_e32 v[100:101], v[84:85]
	v_mov_b64_e32 v[98:99], v[82:83]
	v_mov_b64_e32 v[96:97], v[80:81]
	s_add_i32 s2, s7, 2
	s_cmp_gt_u32 s2, s6
	s_cbranch_scc1 .LBB0_846
	s_branch .LBB0_845

; DI float xhalf_max(float v) { unsigned a = __builtin_bit_cast(unsigned, v), b = a; swap32(a, b); return fmaxf(__builtin_bit_cast(float, a), __builtin_bit_cast(float, b)); }
; DI float fexp2(float x) { return __builtin_amdgcn_exp2f(x); }
; template <int MODE>
; DI void nsa_tile(LAS const unsigned char* buf, const bf16x8 (&qf)[4], f32x16 (&o)[2], float& m, float& l, int kbase0, int t, bool lanesel, float slope2, int c, int hi) {
;     ...
;         float mx = max16(s);
;         mx = xhalf_max(mx);
;         if (__any(mx > m + 8.f)) {
;             const float mn = fmaxf(m, mx), alpha = fexp2(m - mn); m = mn; l *= alpha;
;             o[0] = o[0] * alpha; o[1] = o[1] * alpha;
;         }
.LBB0_850:
	v_max3_f32 v182, v112, v113, v114
	v_max3_f32 v183, v115, v116, v117
	v_max3_f32 v184, v118, v119, v120
	v_max3_f32 v185, v121, v122, v123
	s_nop 0
	v_max3_f32 v182, v182, v124, v125
	v_max3_f32 v183, v183, v126, v127
	s_nop 0
	v_max3_f32 v182, v182, v183, v184
	s_nop 0
	v_max3_f32 v182, v182, v185, v185
	s_nop 0
	v_cmp_gt_f32_e32 vcc, v182, v253
	s_cbranch_vccz .LBB0_852
	v_mov_b32_e32 v183, v182
	s_nop 1
	v_permlane32_swap_b32 v182, v183
	s_nop 0
	v_max_f32_e32 v182, v182, v183
	v_add_f32_e32 v182, v182, v249
	v_max_f32_e32 v182, v182, v182
	v_max_f32_e32 v183, v180, v180
	v_max_f32_e32 v182, v183, v182
	v_sub_f32_e32 v180, v180, v182
	v_exp_f32_e32 v180, v180
	s_nop 0
	v_mul_f32_e32 v161, v161, v180
	v_pk_mul_f32 v[110:111], v[110:111], v[180:181] op_sel_hi:[1,0]
	v_pk_mul_f32 v[108:109], v[108:109], v[180:181] op_sel_hi:[1,0]
	v_pk_mul_f32 v[106:107], v[106:107], v[180:181] op_sel_hi:[1,0]
	v_pk_mul_f32 v[104:105], v[104:105], v[180:181] op_sel_hi:[1,0]
	v_pk_mul_f32 v[102:103], v[102:103], v[180:181] op_sel_hi:[1,0]
	v_pk_mul_f32 v[100:101], v[100:101], v[180:181] op_sel_hi:[1,0]
	v_pk_mul_f32 v[98:99], v[98:99], v[180:181] op_sel_hi:[1,0]
	v_pk_mul_f32 v[96:97], v[96:97], v[180:181] op_sel_hi:[1,0]
	v_pk_mul_f32 v[94:95], v[94:95], v[180:181] op_sel_hi:[1,0]
	v_pk_mul_f32 v[92:93], v[92:93], v[180:181] op_sel_hi:[1,0]
	v_pk_mul_f32 v[90:91], v[90:91], v[180:181] op_sel_hi:[1,0]
	v_pk_mul_f32 v[88:89], v[88:89], v[180:181] op_sel_hi:[1,0]
	v_pk_mul_f32 v[86:87], v[86:87], v[180:181] op_sel_hi:[1,0]
	v_pk_mul_f32 v[84:85], v[84:85], v[180:181] op_sel_hi:[1,0]
	v_pk_mul_f32 v[82:83], v[82:83], v[180:181] op_sel_hi:[1,0]
	v_pk_mul_f32 v[80:81], v[80:81], v[180:181] op_sel_hi:[1,0]
	v_mov_b32_e32 v180, v182
	v_cmp_lt_f32_e32 vcc, 0xdf0ac723, v180
	s_nop 1
	v_cndmask_b32_e32 v250, 0, v180, vcc
	v_mov_b32_e32 v254, 0x41000000
	v_mov_b32_e32 v255, 0xe0ad78ec
	v_cndmask_b32_e32 v253, v255, v254, vcc
	v_sub_f32_e32 v251, v250, v249
	v_mov_b32_e32 v249, v250
	v_sub_f32_e32 v112, v112, v251
	v_sub_f32_e32 v113, v113, v251
	v_sub_f32_e32 v114, v114, v251
	v_sub_f32_e32 v115, v115, v251
	v_sub_f32_e32 v116, v116, v251
	v_sub_f32_e32 v117, v117, v251
	v_sub_f32_e32 v118, v118, v251
	v_sub_f32_e32 v119, v119, v251
	v_sub_f32_e32 v120, v120, v251
	v_sub_f32_e32 v121, v121, v251
	v_sub_f32_e32 v122, v122, v251
	v_sub_f32_e32 v123, v123, v251
	v_sub_f32_e32 v124, v124, v251
	v_sub_f32_e32 v125, v125, v251
	v_sub_f32_e32 v126, v126, v251
	v_sub_f32_e32 v127, v127, v251

; DI float xhalf_max(float v) { unsigned a = __builtin_bit_cast(unsigned, v), b = a; swap32(a, b); return fmaxf(__builtin_bit_cast(float, a), __builtin_bit_cast(float, b)); }
; DI float fexp2(float x) { return __builtin_amdgcn_exp2f(x); }
; template <int MODE>
; DI void nsa_tile(LAS const unsigned char* buf, const bf16x8 (&qf)[4], f32x16 (&o)[2], float& m, float& l, int kbase0, int t, bool lanesel, float slope2, int c, int hi) {
;     ...
;         float mx = max16(s);
;         mx = xhalf_max(mx);
;         if (__any(mx > m + 8.f)) {
;             const float mn = fmaxf(m, mx), alpha = fexp2(m - mn); m = mn; l *= alpha;
;             o[0] = o[0] * alpha; o[1] = o[1] * alpha;
;         }
.LBB0_856:
	v_max3_f32 v181, v112, v113, v114
	v_max3_f32 v182, v115, v116, v117
	v_max3_f32 v183, v118, v119, v120
	v_max3_f32 v184, v121, v122, v123
	s_nop 0
	v_max3_f32 v181, v181, v124, v125
	v_max3_f32 v182, v182, v126, v127
	s_nop 0
	v_max3_f32 v181, v181, v182, v183
	s_nop 0
	v_max3_f32 v181, v181, v184, v184
	s_nop 0
	v_cmp_gt_f32_e32 vcc, v181, v253
	s_cbranch_vccz .LBB0_858
	v_mov_b32_e32 v182, v181
	s_nop 1
	v_permlane32_swap_b32 v181, v182
	s_nop 0
	v_max_f32_e32 v181, v181, v182
	v_add_f32_e32 v181, v181, v249
	v_max_f32_e32 v181, v181, v181
	v_max_f32_e32 v182, v180, v180
	v_max_f32_e32 v181, v182, v181
	v_sub_f32_e32 v180, v180, v181
	v_exp_f32_e32 v180, v180
	s_nop 0
	v_mul_f32_e32 v161, v161, v180
	v_pk_mul_f32 v[110:111], v[110:111], v[180:181] op_sel_hi:[1,0]
	v_pk_mul_f32 v[108:109], v[108:109], v[180:181] op_sel_hi:[1,0]
	v_pk_mul_f32 v[106:107], v[106:107], v[180:181] op_sel_hi:[1,0]
	v_pk_mul_f32 v[104:105], v[104:105], v[180:181] op_sel_hi:[1,0]
	v_pk_mul_f32 v[102:103], v[102:103], v[180:181] op_sel_hi:[1,0]
	v_pk_mul_f32 v[100:101], v[100:101], v[180:181] op_sel_hi:[1,0]
	v_pk_mul_f32 v[98:99], v[98:99], v[180:181] op_sel_hi:[1,0]
	v_pk_mul_f32 v[96:97], v[96:97], v[180:181] op_sel_hi:[1,0]
	v_pk_mul_f32 v[94:95], v[94:95], v[180:181] op_sel_hi:[1,0]
	v_pk_mul_f32 v[92:93], v[92:93], v[180:181] op_sel_hi:[1,0]
	v_pk_mul_f32 v[90:91], v[90:91], v[180:181] op_sel_hi:[1,0]
	v_pk_mul_f32 v[88:89], v[88:89], v[180:181] op_sel_hi:[1,0]
	v_pk_mul_f32 v[86:87], v[86:87], v[180:181] op_sel_hi:[1,0]
	v_pk_mul_f32 v[84:85], v[84:85], v[180:181] op_sel_hi:[1,0]
	v_pk_mul_f32 v[82:83], v[82:83], v[180:181] op_sel_hi:[1,0]
	v_pk_mul_f32 v[80:81], v[80:81], v[180:181] op_sel_hi:[1,0]
	v_mov_b32_e32 v180, v181
	v_cmp_lt_f32_e32 vcc, 0xdf0ac723, v180
	s_nop 1
	v_cndmask_b32_e32 v250, 0, v180, vcc
	v_mov_b32_e32 v254, 0x41000000
	v_mov_b32_e32 v255, 0xe0ad78ec
	v_cndmask_b32_e32 v253, v255, v254, vcc
	v_sub_f32_e32 v251, v250, v249
	v_mov_b32_e32 v249, v250
	v_sub_f32_e32 v112, v112, v251
	v_sub_f32_e32 v113, v113, v251
	v_sub_f32_e32 v114, v114, v251
	v_sub_f32_e32 v115, v115, v251
	v_sub_f32_e32 v116, v116, v251
	v_sub_f32_e32 v117, v117, v251
	v_sub_f32_e32 v118, v118, v251
	v_sub_f32_e32 v119, v119, v251
	v_sub_f32_e32 v120, v120, v251
	v_sub_f32_e32 v121, v121, v251
	v_sub_f32_e32 v122, v122, v251
	v_sub_f32_e32 v123, v123, v251
	v_sub_f32_e32 v124, v124, v251
	v_sub_f32_e32 v125, v125, v251
	v_sub_f32_e32 v126, v126, v251
	v_sub_f32_e32 v127, v127, v251
